# v13: phase-2 log-sigmoid: dropped the denormal-rescale and inf-select logic of logf whose argument is 1+exp2(..) in [1,2] (results bit-identical)
# speedup vs baseline: 1.0118x; 1.0101x over previous
; #define LAS __attribute__((address_space(3)))
; __device__ __forceinline__ float bf2f(unsigned b) { return __uint_as_float(b << 16); }
; __device__ __forceinline__ unsigned f2bf(float f) { unsigned u = __float_as_uint(f); return (u + 0x7fffu + ((u >> 16) & 1u)) >> 16; }
; __device__ __forceinline__ void split8(const f32x4 x0, const f32x4 x1, bf16x8& hi, bf16x8& lo) {
; #pragma unroll
;     for (int j = 0; j < 8; ++j) { const float x = j < 4 ? x0[j & 3] : x1[j & 3]; const unsigned h = f2bf(x); const unsigned l = f2bf(x - bf2f(h)); hi[j] = (short)h; lo[j] = (short)l; }
; }
; __device__ __forceinline__ void phase_gla_pre(const Params& P, LAS unsigned char* lds, bool dry) {
;     ...
;             if (g < 2) { const f32x4 l0 = *(const LAS f32x4*)(Llr + (16 * tt + fr) * 16 + 8 * g), l1 = *(const LAS f32x4*)(Llr + (16 * tt + fr) * 16 + 8 * g + 4); split8(l0, l1, ahi, alo); }
;             f32x4 acc = (f32x4){bg, bg, bg, bg};
;             acc = __builtin_amdgcn_mfma_f32_16x16x32_bf16(alo, bhi, acc, 0, 0, 0); acc = __builtin_amdgcn_mfma_f32_16x16x32_bf16(ahi, blo, acc, 0, 0, 0); acc = __builtin_amdgcn_mfma_f32_16x16x32_bf16(ahi, bhi, acc, 0, 0, 0);
;             float pr[4];
; #pragma unroll
;             for (int r = 0; r < 4; ++r) { const float lg = acc[r]; const float ls = fminf(lg, 0.f) - __logf(1.0f + __expf(-fabsf(lg))); pr[r] = ls * (1.0f / 16.0f) + (r ? pr[r - 1] : 0.f); }
;             const float T = pr[3];
;             const float u1 = __shfl_up(T, 16), s1 = T + (g >= 1 ? u1 : 0.f);
;             const float u2 = __shfl_up(s1, 32), s2 = s1 + (g >= 2 ? u2 : 0.f);
;             const float base = run + (s2 - T); run += __shfl(s2, 48 + fr);
; #pragma unroll
;             for (int r = 0; r < 4; ++r) *(LAS float*)(Lb + (16 * tt + 4 * g + r) * BP + (16 * w + fr) * 4) = base + pr[r];
.Lp2_nowait1:
	v_mov_b32_e32 v140, v20
	v_mov_b32_e32 v141, v21
	v_mov_b32_e32 v142, v22
	v_mov_b32_e32 v143, v23
	v_mov_b32_e32 v144, v24
	v_mov_b32_e32 v145, v25
	v_mov_b32_e32 v146, v26
	v_mov_b32_e32 v147, v27
	v_mov_b32_e32 v148, v28
	s_and_b32 s98, s38, 0xff
	s_cselect_b32 s98, 0, 1
	v_mov_b32_e32 v29, v28
	v_mov_b32_e32 v30, v28
	v_mov_b32_e32 v31, v28
	v_mov_b32_e32 v40, 0
	v_mov_b32_e32 v41, 0
	v_mfma_f32_16x16x32_bf16 v[32:35], v[32:35], v[20:23], v[28:31]
	v_mfma_f32_16x16x32_bf16 v[32:35], v[36:39], v[24:27], v[32:35]
	v_mfma_f32_16x16x32_bf16 v[32:35], v[36:39], v[20:23], v[32:35]
	s_nop 7
	v_max_f32_e32 v36, v32, v32
	v_mul_f32_e64 v32, |v32|, s89
	v_exp_f32_e32 v32, v32
	v_mul_f32_e64 v37, |v33|, s89
	v_exp_f32_e32 v37, v37
	v_min_f32_e32 v36, 0, v36
	v_add_f32_e32 v32, 1.0, v32
	v_add_f32_e32 v37, 1.0, v37
	v_log_f32_e32 v32, v32
	v_log_f32_e32 v37, v37
	v_mul_f32_e32 v39, 0x3f317217, v32
	v_fma_f32 v39, v32, s91, -v39
	v_fmac_f32_e32 v39, 0x3377d1cf, v32
	v_fmac_f32_e32 v39, 0x3f317217, v32
	v_max_f32_e32 v33, v33, v33
	v_min_f32_e32 v33, 0, v33
	v_mov_b32_e32 v32, v39
	v_sub_f32_e32 v32, v36, v32
	v_mul_f32_e32 v36, 0x3f317217, v37
	v_fma_f32 v36, v37, s91, -v36
	v_fmac_f32_e32 v36, 0x3377d1cf, v37
	v_fmac_f32_e32 v36, 0x3f317217, v37
	v_fma_f32 v32, v32, s93, 0
	v_mul_f32_e64 v37, |v34|, s89
	v_exp_f32_e32 v37, v37
	v_sub_f32_e32 v33, v33, v36
	v_mov_b32_e32 v39, 0
	v_add_f32_e32 v36, 1.0, v37
	s_nop 1
	v_log_f32_e32 v36, v36
	v_fmamk_f32 v37, v33, 0x3d800000, v32
	v_max_f32_e32 v33, v34, v34
	v_mul_f32_e32 v34, 0x3f317217, v36
	v_fma_f32 v34, v36, s91, -v34
	v_fmac_f32_e32 v34, 0x3377d1cf, v36
	v_fmac_f32_e32 v34, 0x3f317217, v36
	v_min_f32_e32 v33, 0, v33
	s_nop 0
	v_mul_f32_e64 v36, |v35|, s89
	v_exp_f32_e32 v36, v36
	v_sub_f32_e32 v33, v33, v34
	v_add_u32_e32 v38, 0x8800, v98
	v_add_f32_e32 v34, 1.0, v36
	s_nop 1
	v_log_f32_e32 v34, v34
	v_fmamk_f32 v36, v33, 0x3d800000, v37
	v_max_f32_e32 v33, v35, v35
	v_min_f32_e32 v33, 0, v33
	v_mul_f32_e32 v35, 0x3f317217, v34
	v_fma_f32 v35, v34, s91, -v35
	v_fmac_f32_e32 v35, 0x3377d1cf, v34
	v_fmac_f32_e32 v35, 0x3f317217, v34
	s_nop 1
	v_mov_b32_e32 v34, v35
	v_sub_f32_e32 v33, v33, v34
	v_fmamk_f32 v34, v33, 0x3d800000, v36
	ds_bpermute_b32 v33, v83, v34
	s_waitcnt lgkmcnt(0)
	v_cndmask_b32_e64 v33, v33, 0, s[8:9]
	v_add_f32_e32 v33, v33, v34
	ds_bpermute_b32 v35, v84, v33
	s_waitcnt lgkmcnt(0)
	v_cndmask_b32_e64 v35, 0, v35, s[10:11]
	v_add_f32_e32 v33, v35, v33
	v_sub_f32_e32 v35, v33, v34
	ds_bpermute_b32 v33, v85, v33
	v_add_f32_e32 v35, 0, v35
	v_add_f32_e32 v32, v32, v35
	v_add_f32_e32 v37, v37, v35
	ds_write2_b32 v38, v32, v37 offset1:132
	v_add_f32_e32 v32, v36, v35
	v_add_f32_e32 v34, v34, v35
	v_add_u32_e32 v35, 0x8c00, v98
	ds_write2_b32 v35, v32, v34 offset0:8 offset1:140
	v_mov_b32_e32 v32, 0
	v_mov_b32_e32 v34, 0
	v_mov_b32_e32 v35, 0
	v_mov_b32_e32 v36, 0
	v_mov_b32_e32 v37, 0
	v_mov_b32_e32 v38, 0
	s_and_saveexec_b64 s[36:37], s[6:7]
	s_cbranch_execz .LBB0_488
	ds_read_b128 v[34:37], v96 offset:1024
	ds_read_b128 v[38:41], v96 offset:1040
	s_waitcnt lgkmcnt(1)
	v_and_b32_sdwa v42, v35, v95 dst_sel:DWORD dst_unused:UNUSED_PAD src0_sel:WORD_1 src1_sel:DWORD
	v_and_b32_sdwa v43, v34, v95 dst_sel:DWORD dst_unused:UNUSED_PAD src0_sel:WORD_1 src1_sel:DWORD
	v_add3_u32 v44, v35, v42, s86
	v_add3_u32 v45, v34, v43, s86
	v_and_b32_e32 v43, 0xffff0000, v44
	v_and_b32_e32 v42, 0xffff0000, v45
	v_cvt_pk_bf16_f32 v196, v34, v35
	v_pk_add_f32 v[34:35], v[34:35], v[42:43] neg_lo:[0,1] neg_hi:[0,1]
	v_and_b32_sdwa v42, v37, v95 dst_sel:DWORD dst_unused:UNUSED_PAD src0_sel:WORD_1 src1_sel:DWORD
	v_and_b32_sdwa v43, v36, v95 dst_sel:DWORD dst_unused:UNUSED_PAD src0_sel:WORD_1 src1_sel:DWORD
	v_add3_u32 v46, v37, v42, s86
	v_add3_u32 v47, v36, v43, s86
	v_and_b32_e32 v43, 0xffff0000, v46
	v_and_b32_e32 v42, 0xffff0000, v47
	v_cvt_pk_bf16_f32 v197, v36, v37
	v_pk_add_f32 v[36:37], v[36:37], v[42:43] neg_lo:[0,1] neg_hi:[0,1]
	s_waitcnt lgkmcnt(0)
	v_and_b32_sdwa v42, v39, v95 dst_sel:DWORD dst_unused:UNUSED_PAD src0_sel:WORD_1 src1_sel:DWORD
	v_and_b32_sdwa v43, v38, v95 dst_sel:DWORD dst_unused:UNUSED_PAD src0_sel:WORD_1 src1_sel:DWORD
	v_add3_u32 v60, v39, v42, s86
	v_add3_u32 v61, v38, v43, s86
	v_and_b32_e32 v43, 0xffff0000, v60
	v_and_b32_e32 v42, 0xffff0000, v61
	v_cvt_pk_bf16_f32 v198, v38, v39
	v_pk_add_f32 v[38:39], v[38:39], v[42:43] neg_lo:[0,1] neg_hi:[0,1]
	v_and_b32_sdwa v42, v41, v95 dst_sel:DWORD dst_unused:UNUSED_PAD src0_sel:WORD_1 src1_sel:DWORD
	v_and_b32_sdwa v43, v40, v95 dst_sel:DWORD dst_unused:UNUSED_PAD src0_sel:WORD_1 src1_sel:DWORD
	v_add3_u32 v62, v41, v42, s86
	v_add3_u32 v63, v40, v43, s86
	v_and_b32_e32 v43, 0xffff0000, v62
	v_and_b32_e32 v42, 0xffff0000, v63
	v_cvt_pk_bf16_f32 v199, v40, v41
	v_pk_add_f32 v[40:41], v[40:41], v[42:43] neg_lo:[0,1] neg_hi:[0,1]
	s_nop 0
	v_cvt_pk_bf16_f32 v193, v40, v41
	v_cvt_pk_bf16_f32 v192, v38, v39
	v_cvt_pk_bf16_f32 v191, v36, v37
	v_cvt_pk_bf16_f32 v190, v34, v35
	v_mov_b32_e32 v34, v190
	v_mov_b32_e32 v35, v191
	v_mov_b32_e32 v36, v192
	v_mov_b32_e32 v37, v193
	v_mov_b32_e32 v38, v196
	v_mov_b32_e32 v39, v197
	v_mov_b32_e32 v40, v198
	v_mov_b32_e32 v41, v199
; #define LAS __attribute__((address_space(3)))
; __device__ __forceinline__ float bf2f(unsigned b) { return __uint_as_float(b << 16); }
; __device__ __forceinline__ unsigned f2bf(float f) { unsigned u = __float_as_uint(f); return (u + 0x7fffu + ((u >> 16) & 1u)) >> 16; }
; __device__ __forceinline__ void split8(const f32x4 x0, const f32x4 x1, bf16x8& hi, bf16x8& lo) {
; #pragma unroll
;     for (int j = 0; j < 8; ++j) { const float x = j < 4 ? x0[j & 3] : x1[j & 3]; const unsigned h = f2bf(x); const unsigned l = f2bf(x - bf2f(h)); hi[j] = (short)h; lo[j] = (short)l; }
; }
; __device__ __forceinline__ void phase_gla_pre(const Params& P, LAS unsigned char* lds, bool dry) {
;     ...
;             if (g < 2) { const f32x4 l0 = *(const LAS f32x4*)(Llr + (16 * tt + fr) * 16 + 8 * g), l1 = *(const LAS f32x4*)(Llr + (16 * tt + fr) * 16 + 8 * g + 4); split8(l0, l1, ahi, alo); }
;             f32x4 acc = (f32x4){bg, bg, bg, bg};
;             acc = __builtin_amdgcn_mfma_f32_16x16x32_bf16(alo, bhi, acc, 0, 0, 0); acc = __builtin_amdgcn_mfma_f32_16x16x32_bf16(ahi, blo, acc, 0, 0, 0); acc = __builtin_amdgcn_mfma_f32_16x16x32_bf16(ahi, bhi, acc, 0, 0, 0);
;             float pr[4];
; #pragma unroll
;             for (int r = 0; r < 4; ++r) { const float lg = acc[r]; const float ls = fminf(lg, 0.f) - __logf(1.0f + __expf(-fabsf(lg))); pr[r] = ls * (1.0f / 16.0f) + (r ? pr[r - 1] : 0.f); }
;             const float T = pr[3];
;             const float u1 = __shfl_up(T, 16), s1 = T + (g >= 1 ? u1 : 0.f);
;             const float u2 = __shfl_up(s1, 32), s2 = s1 + (g >= 2 ? u2 : 0.f);
;             const float base = run + (s2 - T); run += __shfl(s2, 48 + fr);
; #pragma unroll
;             for (int r = 0; r < 4; ++r) *(LAS float*)(Lb + (16 * tt + 4 * g + r) * BP + (16 * w + fr) * 4) = base + pr[r];
.LBB0_488:
	s_or_b64 exec, exec, s[36:37]
	v_mfma_f32_16x16x32_bf16 v[34:37], v[34:37], v[20:23], v[28:31]
	v_mfma_f32_16x16x32_bf16 v[34:37], v[38:41], v[24:27], v[34:37]
	v_mfma_f32_16x16x32_bf16 v[34:37], v[38:41], v[20:23], v[34:37]
	s_nop 7
	v_max_f32_e32 v38, v34, v34
	v_mul_f32_e64 v34, |v34|, s89
	v_exp_f32_e32 v34, v34
	v_mul_f32_e64 v39, |v35|, s89
	v_exp_f32_e32 v39, v39
	v_min_f32_e32 v38, 0, v38
	v_add_f32_e32 v34, 1.0, v34
	v_add_f32_e32 v39, 1.0, v39
	v_log_f32_e32 v34, v34
	v_log_f32_e32 v39, v39
	v_mul_f32_e32 v41, 0x3f317217, v34
	v_fma_f32 v41, v34, s91, -v41
	v_fmac_f32_e32 v41, 0x3377d1cf, v34
	v_fmac_f32_e32 v41, 0x3f317217, v34
	v_mul_f32_e32 v42, 0x3f317217, v39
	v_max_f32_e32 v35, v35, v35
	v_mov_b32_e32 v34, v41
	v_sub_f32_e32 v34, v38, v34
	v_fma_f32 v38, v39, s91, -v42
	v_fmac_f32_e32 v38, 0x3377d1cf, v39
	v_fmac_f32_e32 v38, 0x3f317217, v39
	v_min_f32_e32 v35, 0, v35
	v_mul_f32_e64 v39, |v36|, s89
	v_exp_f32_e32 v39, v39
	v_sub_f32_e32 v35, v35, v38
	v_max_f32_e32 v36, v36, v36
	v_add_f32_e32 v38, 1.0, v39
	v_min_f32_e32 v36, 0, v36
	v_fma_f32 v34, v34, s93, 0
	v_log_f32_e32 v38, v38
	v_fmamk_f32 v35, v35, 0x3d800000, v34
	v_mul_f32_e32 v39, 0x3f317217, v38
	v_fma_f32 v39, v38, s91, -v39
	v_fmac_f32_e32 v39, 0x3377d1cf, v38
	v_fmac_f32_e32 v39, 0x3f317217, v38
	s_nop 1
	v_mov_b32_e32 v38, v39
	v_mul_f32_e64 v39, |v37|, s89
	v_exp_f32_e32 v39, v39
	v_sub_f32_e32 v36, v36, v38
	v_max_f32_e32 v37, v37, v37
	v_add_f32_e32 v38, 1.0, v39
	v_min_f32_e32 v37, 0, v37
	v_fmamk_f32 v36, v36, 0x3d800000, v35
	v_log_f32_e32 v38, v38
	s_waitcnt lgkmcnt(2)
	v_add_f32_e32 v40, 0, v33
	v_mul_f32_e32 v39, 0x3f317217, v38
	v_fma_f32 v39, v38, s91, -v39
	v_fmac_f32_e32 v39, 0x3377d1cf, v38
	v_fmac_f32_e32 v39, 0x3f317217, v38
	s_nop 1
	v_mov_b32_e32 v38, v39
	v_sub_f32_e32 v37, v37, v38
	v_fmamk_f32 v37, v37, 0x3d800000, v36
	ds_bpermute_b32 v38, v83, v37
	s_waitcnt lgkmcnt(0)
	v_cndmask_b32_e64 v38, v38, 0, s[8:9]
	v_add_f32_e32 v38, v38, v37
	ds_bpermute_b32 v39, v84, v38
	s_waitcnt lgkmcnt(0)
	v_cndmask_b32_e64 v33, 0, v39, s[10:11]
	v_add_f32_e32 v33, v33, v38
	v_sub_f32_e32 v38, v33, v37
	ds_bpermute_b32 v41, v85, v33
	v_add_f32_e32 v38, v40, v38
	v_add_f32_e32 v33, v34, v38
	v_add_f32_e32 v34, v35, v38
	v_add_u32_e32 v35, 0xa800, v98
	ds_write2_b32 v35, v33, v34 offset0:64 offset1:196
	v_add_f32_e32 v33, v36, v38
	v_add_f32_e32 v34, v37, v38
	v_add_u32_e32 v35, 0xac00, v98
	ds_write2_b32 v35, v33, v34 offset0:72 offset1:204
	v_mov_b32_e32 v33, 0
	v_mov_b32_e32 v34, 0
	v_mov_b32_e32 v35, 0
	v_mov_b32_e32 v36, 0
	v_mov_b32_e32 v37, 0
	v_mov_b32_e32 v38, 0
	v_mov_b32_e32 v39, 0
	s_and_saveexec_b64 s[36:37], s[6:7]
	s_cbranch_execz .LBB0_490
	ds_read_b128 v[32:35], v96 offset:2048
	ds_read_b128 v[36:39], v96 offset:2064
	s_waitcnt lgkmcnt(1)
	v_and_b32_sdwa v42, v33, v95 dst_sel:DWORD dst_unused:UNUSED_PAD src0_sel:WORD_1 src1_sel:DWORD
	v_and_b32_sdwa v43, v32, v95 dst_sel:DWORD dst_unused:UNUSED_PAD src0_sel:WORD_1 src1_sel:DWORD
	v_add3_u32 v44, v33, v42, s86
	v_add3_u32 v45, v32, v43, s86
	v_and_b32_e32 v43, 0xffff0000, v44
	v_and_b32_e32 v42, 0xffff0000, v45
	v_cvt_pk_bf16_f32 v204, v32, v33
	v_pk_add_f32 v[32:33], v[32:33], v[42:43] neg_lo:[0,1] neg_hi:[0,1]
	v_and_b32_sdwa v42, v35, v95 dst_sel:DWORD dst_unused:UNUSED_PAD src0_sel:WORD_1 src1_sel:DWORD
	v_and_b32_sdwa v43, v34, v95 dst_sel:DWORD dst_unused:UNUSED_PAD src0_sel:WORD_1 src1_sel:DWORD
	v_add3_u32 v46, v35, v42, s86
	v_add3_u32 v47, v34, v43, s86
	v_and_b32_e32 v43, 0xffff0000, v46
	v_and_b32_e32 v42, 0xffff0000, v47
	v_cvt_pk_bf16_f32 v205, v34, v35
	v_pk_add_f32 v[34:35], v[34:35], v[42:43] neg_lo:[0,1] neg_hi:[0,1]
	s_waitcnt lgkmcnt(0)
	v_and_b32_sdwa v42, v37, v95 dst_sel:DWORD dst_unused:UNUSED_PAD src0_sel:WORD_1 src1_sel:DWORD
	v_and_b32_sdwa v43, v36, v95 dst_sel:DWORD dst_unused:UNUSED_PAD src0_sel:WORD_1 src1_sel:DWORD
	v_add3_u32 v60, v37, v42, s86
	v_add3_u32 v61, v36, v43, s86
	v_and_b32_e32 v43, 0xffff0000, v60
	v_and_b32_e32 v42, 0xffff0000, v61
	v_cvt_pk_bf16_f32 v206, v36, v37
	v_pk_add_f32 v[36:37], v[36:37], v[42:43] neg_lo:[0,1] neg_hi:[0,1]
	v_and_b32_sdwa v42, v39, v95 dst_sel:DWORD dst_unused:UNUSED_PAD src0_sel:WORD_1 src1_sel:DWORD
	v_and_b32_sdwa v43, v38, v95 dst_sel:DWORD dst_unused:UNUSED_PAD src0_sel:WORD_1 src1_sel:DWORD
	v_add3_u32 v62, v39, v42, s86
	v_add3_u32 v63, v38, v43, s86
	v_and_b32_e32 v43, 0xffff0000, v62
	v_and_b32_e32 v42, 0xffff0000, v63
	v_cvt_pk_bf16_f32 v208, v38, v39
	v_pk_add_f32 v[38:39], v[38:39], v[42:43] neg_lo:[0,1] neg_hi:[0,1]
	s_nop 0
	v_cvt_pk_bf16_f32 v203, v38, v39
	v_cvt_pk_bf16_f32 v202, v36, v37
	v_cvt_pk_bf16_f32 v201, v34, v35
	v_cvt_pk_bf16_f32 v200, v32, v33
	v_mov_b32_e32 v32, v200
	v_mov_b32_e32 v33, v201
	v_mov_b32_e32 v34, v202
	v_mov_b32_e32 v35, v203
	v_mov_b32_e32 v36, v204
	v_mov_b32_e32 v37, v205
	v_mov_b32_e32 v38, v206
	v_mov_b32_e32 v39, v208
; #define LAS __attribute__((address_space(3)))
; __device__ __forceinline__ float bf2f(unsigned b) { return __uint_as_float(b << 16); }
; __device__ __forceinline__ unsigned f2bf(float f) { unsigned u = __float_as_uint(f); return (u + 0x7fffu + ((u >> 16) & 1u)) >> 16; }
; __device__ __forceinline__ void split8(const f32x4 x0, const f32x4 x1, bf16x8& hi, bf16x8& lo) {
; #pragma unroll
;     for (int j = 0; j < 8; ++j) { const float x = j < 4 ? x0[j & 3] : x1[j & 3]; const unsigned h = f2bf(x); const unsigned l = f2bf(x - bf2f(h)); hi[j] = (short)h; lo[j] = (short)l; }
; }
; __device__ __forceinline__ void phase_gla_pre(const Params& P, LAS unsigned char* lds, bool dry) {
;     ...
;             if (g < 2) { const f32x4 l0 = *(const LAS f32x4*)(Llr + (16 * tt + fr) * 16 + 8 * g), l1 = *(const LAS f32x4*)(Llr + (16 * tt + fr) * 16 + 8 * g + 4); split8(l0, l1, ahi, alo); }
;             f32x4 acc = (f32x4){bg, bg, bg, bg};
;             acc = __builtin_amdgcn_mfma_f32_16x16x32_bf16(alo, bhi, acc, 0, 0, 0); acc = __builtin_amdgcn_mfma_f32_16x16x32_bf16(ahi, blo, acc, 0, 0, 0); acc = __builtin_amdgcn_mfma_f32_16x16x32_bf16(ahi, bhi, acc, 0, 0, 0);
;             float pr[4];
; #pragma unroll
;             for (int r = 0; r < 4; ++r) { const float lg = acc[r]; const float ls = fminf(lg, 0.f) - __logf(1.0f + __expf(-fabsf(lg))); pr[r] = ls * (1.0f / 16.0f) + (r ? pr[r - 1] : 0.f); }
;             const float T = pr[3];
;             const float u1 = __shfl_up(T, 16), s1 = T + (g >= 1 ? u1 : 0.f);
;             const float u2 = __shfl_up(s1, 32), s2 = s1 + (g >= 2 ? u2 : 0.f);
;             const float base = run + (s2 - T); run += __shfl(s2, 48 + fr);
; #pragma unroll
;             for (int r = 0; r < 4; ++r) *(LAS float*)(Lb + (16 * tt + 4 * g + r) * BP + (16 * w + fr) * 4) = base + pr[r];
.LBB0_490:
	s_or_b64 exec, exec, s[36:37]
	v_mfma_f32_16x16x32_bf16 v[32:35], v[32:35], v[20:23], v[28:31]
	s_waitcnt lgkmcnt(2)
	v_add_f32_e32 v40, v40, v41
	v_mfma_f32_16x16x32_bf16 v[32:35], v[36:39], v[24:27], v[32:35]
	v_mfma_f32_16x16x32_bf16 v[32:35], v[36:39], v[20:23], v[32:35]
	s_nop 7
	v_max_f32_e32 v36, v32, v32
	v_mul_f32_e64 v32, |v32|, s89
	v_exp_f32_e32 v32, v32
	v_mul_f32_e64 v37, |v33|, s89
	v_exp_f32_e32 v37, v37
	v_min_f32_e32 v36, 0, v36
	v_add_f32_e32 v32, 1.0, v32
	v_add_f32_e32 v37, 1.0, v37
	v_log_f32_e32 v32, v32
	v_log_f32_e32 v37, v37
	v_mul_f32_e32 v39, 0x3f317217, v32
	v_fma_f32 v39, v32, s91, -v39
	v_fmac_f32_e32 v39, 0x3377d1cf, v32
	v_fmac_f32_e32 v39, 0x3f317217, v32
	v_mul_f32_e32 v42, 0x3f317217, v37
	v_max_f32_e32 v33, v33, v33
	v_mov_b32_e32 v32, v39
	v_sub_f32_e32 v32, v36, v32
	v_fma_f32 v36, v37, s91, -v42
	v_fmac_f32_e32 v36, 0x3377d1cf, v37
	v_fmac_f32_e32 v36, 0x3f317217, v37
	v_min_f32_e32 v33, 0, v33
	v_mul_f32_e64 v37, |v34|, s89
	v_exp_f32_e32 v37, v37
	v_sub_f32_e32 v33, v33, v36
	v_max_f32_e32 v34, v34, v34
	v_add_f32_e32 v36, 1.0, v37
	v_min_f32_e32 v34, 0, v34
	v_fma_f32 v32, v32, s93, 0
	v_log_f32_e32 v36, v36
	v_fmamk_f32 v33, v33, 0x3d800000, v32
	v_mov_b32_e32 v39, 0
	v_mul_f32_e32 v37, 0x3f317217, v36
	v_fma_f32 v37, v36, s91, -v37
	v_fmac_f32_e32 v37, 0x3377d1cf, v36
	v_fmac_f32_e32 v37, 0x3f317217, v36
	s_nop 1
	v_mov_b32_e32 v36, v37
	v_mul_f32_e64 v37, |v35|, s89
	v_exp_f32_e32 v37, v37
	v_sub_f32_e32 v34, v34, v36
	v_max_f32_e32 v35, v35, v35
	v_add_f32_e32 v36, 1.0, v37
	v_min_f32_e32 v35, 0, v35
	v_fmamk_f32 v34, v34, 0x3d800000, v33
	v_log_f32_e32 v36, v36
	v_mov_b32_e32 v38, 0
	v_mul_f32_e32 v37, 0x3f317217, v36
	v_fma_f32 v37, v36, s91, -v37
	v_fmac_f32_e32 v37, 0x3377d1cf, v36
	v_fmac_f32_e32 v37, 0x3f317217, v36
	s_nop 1
	v_mov_b32_e32 v36, v37
	v_sub_f32_e32 v35, v35, v36
	v_fmamk_f32 v35, v35, 0x3d800000, v34
	ds_bpermute_b32 v36, v83, v35
	s_waitcnt lgkmcnt(0)
	v_cndmask_b32_e64 v36, v36, 0, s[8:9]
	v_add_f32_e32 v36, v36, v35
	ds_bpermute_b32 v37, v84, v36
	s_waitcnt lgkmcnt(0)
	v_cndmask_b32_e64 v37, 0, v37, s[10:11]
	v_add_f32_e32 v36, v37, v36
	v_sub_f32_e32 v37, v36, v35
	ds_bpermute_b32 v41, v85, v36
	v_add_f32_e32 v37, v40, v37
	v_add_f32_e32 v32, v32, v37
	v_add_f32_e32 v33, v33, v37
	v_add_u32_e32 v36, 0xca00, v98
	ds_write2_b32 v36, v32, v33 offset1:132
	v_add_f32_e32 v32, v34, v37
	v_add_f32_e32 v33, v35, v37
	v_add_u32_e32 v34, 0xce00, v98
	ds_write2_b32 v34, v32, v33 offset0:8 offset1:140
	v_mov_b32_e32 v32, 0
	v_mov_b32_e32 v33, 0
	v_mov_b32_e32 v34, 0
	v_mov_b32_e32 v35, 0
	v_mov_b32_e32 v36, 0
	v_mov_b32_e32 v37, 0
	s_and_saveexec_b64 s[36:37], s[6:7]
	s_cbranch_execz .LBB0_492
	ds_read_b128 v[32:35], v96 offset:3072
	ds_read_b128 v[36:39], v96 offset:3088
	s_waitcnt lgkmcnt(1)
	v_and_b32_sdwa v42, v33, v95 dst_sel:DWORD dst_unused:UNUSED_PAD src0_sel:WORD_1 src1_sel:DWORD
	v_and_b32_sdwa v43, v32, v95 dst_sel:DWORD dst_unused:UNUSED_PAD src0_sel:WORD_1 src1_sel:DWORD
	v_add3_u32 v44, v33, v42, s86
	v_add3_u32 v45, v32, v43, s86
	v_and_b32_e32 v43, 0xffff0000, v44
	v_and_b32_e32 v42, 0xffff0000, v45
	v_cvt_pk_bf16_f32 v214, v32, v33
	v_pk_add_f32 v[32:33], v[32:33], v[42:43] neg_lo:[0,1] neg_hi:[0,1]
	v_and_b32_sdwa v42, v35, v95 dst_sel:DWORD dst_unused:UNUSED_PAD src0_sel:WORD_1 src1_sel:DWORD
	v_and_b32_sdwa v43, v34, v95 dst_sel:DWORD dst_unused:UNUSED_PAD src0_sel:WORD_1 src1_sel:DWORD
	v_add3_u32 v46, v35, v42, s86
	v_add3_u32 v47, v34, v43, s86
	v_and_b32_e32 v43, 0xffff0000, v46
	v_and_b32_e32 v42, 0xffff0000, v47
	v_cvt_pk_bf16_f32 v216, v34, v35
	v_pk_add_f32 v[34:35], v[34:35], v[42:43] neg_lo:[0,1] neg_hi:[0,1]
	s_waitcnt lgkmcnt(0)
	v_and_b32_sdwa v42, v37, v95 dst_sel:DWORD dst_unused:UNUSED_PAD src0_sel:WORD_1 src1_sel:DWORD
	v_and_b32_sdwa v43, v36, v95 dst_sel:DWORD dst_unused:UNUSED_PAD src0_sel:WORD_1 src1_sel:DWORD
	v_add3_u32 v60, v37, v42, s86
	v_add3_u32 v61, v36, v43, s86
	v_and_b32_e32 v43, 0xffff0000, v60
	v_and_b32_e32 v42, 0xffff0000, v61
	v_cvt_pk_bf16_f32 v217, v36, v37
	v_pk_add_f32 v[36:37], v[36:37], v[42:43] neg_lo:[0,1] neg_hi:[0,1]
	v_and_b32_sdwa v42, v39, v95 dst_sel:DWORD dst_unused:UNUSED_PAD src0_sel:WORD_1 src1_sel:DWORD
	v_and_b32_sdwa v43, v38, v95 dst_sel:DWORD dst_unused:UNUSED_PAD src0_sel:WORD_1 src1_sel:DWORD
	v_add3_u32 v62, v39, v42, s86
	v_add3_u32 v63, v38, v43, s86
	v_and_b32_e32 v43, 0xffff0000, v62
	v_and_b32_e32 v42, 0xffff0000, v63
	v_cvt_pk_bf16_f32 v218, v38, v39
	v_pk_add_f32 v[38:39], v[38:39], v[42:43] neg_lo:[0,1] neg_hi:[0,1]
	s_nop 0
	v_cvt_pk_bf16_f32 v213, v38, v39
	v_cvt_pk_bf16_f32 v212, v36, v37
	v_cvt_pk_bf16_f32 v210, v34, v35
	v_cvt_pk_bf16_f32 v209, v32, v33
	v_mov_b32_e32 v32, v209
	v_mov_b32_e32 v33, v210
	v_mov_b32_e32 v34, v212
	v_mov_b32_e32 v35, v213
	v_mov_b32_e32 v36, v214
	v_mov_b32_e32 v37, v216
	v_mov_b32_e32 v38, v217
	v_mov_b32_e32 v39, v218
; #define LAS __attribute__((address_space(3)))
; __device__ __forceinline__ float bflo(unsigned w) { return __uint_as_float(w << 16); }
; __device__ __forceinline__ float bfhi(unsigned w) { return __uint_as_float(w & 0xffff0000u); }
; __device__ __forceinline__ void phase_gla_pre(const Params& P, LAS unsigned char* lds, bool dry) {
;     ...
;             acc = __builtin_amdgcn_mfma_f32_16x16x32_bf16(alo, bhi, acc, 0, 0, 0); acc = __builtin_amdgcn_mfma_f32_16x16x32_bf16(ahi, blo, acc, 0, 0, 0); acc = __builtin_amdgcn_mfma_f32_16x16x32_bf16(ahi, bhi, acc, 0, 0, 0);
;             float pr[4];
; #pragma unroll
;             for (int r = 0; r < 4; ++r) { const float lg = acc[r]; const float ls = fminf(lg, 0.f) - __logf(1.0f + __expf(-fabsf(lg))); pr[r] = ls * (1.0f / 16.0f) + (r ? pr[r - 1] : 0.f); }
;             const float T = pr[3];
;             const float u1 = __shfl_up(T, 16), s1 = T + (g >= 1 ? u1 : 0.f);
;             const float u2 = __shfl_up(s1, 32), s2 = s1 + (g >= 2 ? u2 : 0.f);
;             const float base = run + (s2 - T); run += __shfl(s2, 48 + fr);
; #pragma unroll
;             for (int r = 0; r < 4; ++r) *(LAS float*)(Lb + (16 * tt + 4 * g + r) * BP + (16 * w + fr) * 4) = base + pr[r];
;         }
;         __syncthreads();
;         {
;             f32x4 bb[4], bm[4], bl[4];
; #pragma unroll
;             for (int i = 0; i < 4; ++i) { bb[i] = *(const LAS f32x4*)(Lb + te * BP + (16 * kc + 4 * i) * 4); bm[i] = *(const LAS f32x4*)(Lb + 31 * BP + (16 * kc + 4 * i) * 4); bl[i] = *(const LAS f32x4*)(Lb + 63 * BP + (16 * kc + 4 * i) * 4); }
;             unsigned oqi[8], oki[8], oqd[8], oks[8];
; #pragma unroll
;             for (int e2 = 0; e2 < 8; ++e2) {
;                 const unsigned qw = e2 < 4 ? rq[0][e2] : rq[1][e2 - 4], kw = e2 < 4 ? rk[0][e2] : rk[1][e2 - 4];
;                 float vqi[2], vki[2], vqd[2], vks[2];
; #pragma unroll
;                 for (int hh = 0; hh < 2; ++hh) {
;                     const int e = 2 * e2 + hh; const float bv = bb[e >> 2][e & 3], bmv = bm[e >> 2][e & 3], blv = bl[e >> 2][e & 3];
;                     const float qv = hh ? bfhi(qw) : bflo(qw), kv = hh ? bfhi(kw) : bflo(kw);
;                     const float e1 = __expf(bv - bmv);
;                     vqi[hh] = qv * e1; vki[hh] = kv * __builtin_amdgcn_rcpf(e1); vqd[hh] = qv * __expf(bv); vks[hh] = kv * __expf(blv - bv);
.LBB0_492:
	s_or_b64 exec, exec, s[36:37]
	v_mfma_f32_16x16x32_bf16 v[28:31], v[32:35], v[20:23], v[28:31]
	v_and_b32_e32 v111, 0xffff0000, v5
	v_and_b32_e32 v110, 0xffff0000, v4
	v_and_b32_e32 v117, 0xffff0000, v13
	v_mfma_f32_16x16x32_bf16 v[24:27], v[36:39], v[24:27], v[28:31]
	v_and_b32_e32 v116, 0xffff0000, v12
	v_and_b32_e32 v121, 0xffff0000, v7
	v_and_b32_e32 v120, 0xffff0000, v6
	v_mfma_f32_16x16x32_bf16 v[20:23], v[36:39], v[20:23], v[24:27]
	v_and_b32_e32 v127, 0xffff0000, v17
	v_and_b32_e32 v126, 0xffff0000, v16
	v_lshlrev_b32_e32 v125, 16, v17
	v_lshlrev_b32_e32 v124, 16, v16
	v_lshlrev_b32_e32 v133, 16, v11
	s_nop 2
	v_max_f32_e32 v24, v20, v20
	v_mul_f32_e64 v20, |v20|, s89
	v_exp_f32_e32 v20, v20
	v_mul_f32_e64 v25, |v21|, s89
	v_exp_f32_e32 v25, v25
	v_min_f32_e32 v24, 0, v24
	v_add_f32_e32 v20, 1.0, v20
	v_add_f32_e32 v25, 1.0, v25
	v_log_f32_e32 v20, v20
	v_log_f32_e32 v25, v25
	v_mul_f32_e32 v27, 0x3f317217, v20
	v_fma_f32 v27, v20, s91, -v27
	v_fmac_f32_e32 v27, 0x3377d1cf, v20
	v_fmac_f32_e32 v27, 0x3f317217, v20
	v_mul_f32_e32 v28, 0x3f317217, v25
	v_max_f32_e32 v21, v21, v21
	v_mov_b32_e32 v20, v27
	v_sub_f32_e32 v20, v24, v20
	v_fma_f32 v24, v25, s91, -v28
	v_fmac_f32_e32 v24, 0x3377d1cf, v25
	v_fmac_f32_e32 v24, 0x3f317217, v25
	v_min_f32_e32 v21, 0, v21
	v_mul_f32_e64 v25, |v22|, s89
	v_exp_f32_e32 v25, v25
	v_sub_f32_e32 v21, v21, v24
	v_max_f32_e32 v22, v22, v22
	v_add_f32_e32 v24, 1.0, v25
	v_min_f32_e32 v22, 0, v22
	v_fma_f32 v20, v20, s93, 0
	v_log_f32_e32 v24, v24
	v_fmamk_f32 v21, v21, 0x3d800000, v20
	v_lshlrev_b32_e32 v132, 16, v10
	v_mul_f32_e32 v25, 0x3f317217, v24
	v_fma_f32 v25, v24, s91, -v25
	v_fmac_f32_e32 v25, 0x3377d1cf, v24
	v_fmac_f32_e32 v25, 0x3f317217, v24
	v_and_b32_e32 v135, 0xffff0000, v11
	v_and_b32_e32 v134, 0xffff0000, v10
	v_mov_b32_e32 v24, v25
	v_mul_f32_e64 v25, |v23|, s89
	v_exp_f32_e32 v25, v25
	v_sub_f32_e32 v22, v22, v24
	v_max_f32_e32 v23, v23, v23
	v_add_f32_e32 v24, 1.0, v25
	v_min_f32_e32 v23, 0, v23
	v_fmamk_f32 v22, v22, 0x3d800000, v21
	v_log_f32_e32 v24, v24
	s_waitcnt lgkmcnt(2)
	v_add_f32_e32 v26, v40, v41
	s_and_b32 s74, s1, 0xfc0
	s_ashr_i32 s83, s82, 31
	v_mul_f32_e32 v25, 0x3f317217, v24
	v_fma_f32 v25, v24, s91, -v25
	v_fmac_f32_e32 v25, 0x3377d1cf, v24
	v_fmac_f32_e32 v25, 0x3f317217, v24
	s_nop 1
	v_mov_b32_e32 v24, v25
	v_sub_f32_e32 v23, v23, v24
	v_fmamk_f32 v23, v23, 0x3d800000, v22
	ds_bpermute_b32 v24, v83, v23
	s_lshl_b64 s[36:37], s[82:83], 20
	s_waitcnt lgkmcnt(0)
	v_cndmask_b32_e64 v24, v24, 0, s[8:9]
	v_add_f32_e32 v24, v24, v23
	ds_bpermute_b32 v25, v84, v24
	s_waitcnt lgkmcnt(0)
	v_cndmask_b32_e64 v25, 0, v25, s[10:11]
	v_add_f32_e32 v24, v25, v24
	v_sub_f32_e32 v24, v24, v23
	v_add_f32_e32 v24, v26, v24
	v_add_f32_e32 v20, v20, v24
	v_add_f32_e32 v21, v21, v24
	v_add_u32_e32 v25, 0xea00, v98
	ds_write2_b32 v25, v20, v21 offset0:64 offset1:196
	v_add_f32_e32 v20, v22, v24
	v_add_f32_e32 v21, v23, v24
	v_add_u32_e32 v22, 0xee00, v98
	ds_write2_b32 v22, v20, v21 offset0:72 offset1:204
	v_add_u32_e32 v22, s94, v87
	s_waitcnt lgkmcnt(0)
	s_barrier
	v_add_u32_e32 v20, v86, v87
	v_add_u32_e32 v21, 0, v87
	ds_read_b128 v[32:35], v22
	ds_read_b128 v[24:27], v89
	ds_read_b128 v[60:63], v21 offset:51184
	ds_read_b128 v[64:67], v20 offset:34816
	ds_read_b128 v[74:77], v20 offset:34832
	ds_read_b128 v[44:47], v20 offset:34848
	ds_read_b128 v[36:39], v20 offset:34864
	ds_read_b128 v[100:103], v21 offset:51200
	s_waitcnt lgkmcnt(4)
	v_sub_f32_e32 v61, v65, v61
	v_mul_f32_e32 v61, 0x3fb8aa3b, v61
	v_sub_f32_e32 v63, v67, v63
	v_exp_f32_e32 v72, v61
	v_sub_f32_e32 v61, v32, v64
	v_mul_f32_e32 v63, 0x3fb8aa3b, v63
	v_mul_f32_e32 v61, 0x3fb8aa3b, v61
	v_exp_f32_e32 v73, v63
	v_exp_f32_e32 v78, v61
	v_mul_f32_e32 v61, 0x3fb8aa3b, v65
	v_sub_f32_e32 v20, v64, v60
	v_exp_f32_e32 v108, v61
	v_sub_f32_e32 v61, v66, v62
	v_mul_f32_e32 v20, 0x3fb8aa3b, v20
	v_mul_f32_e32 v69, 0x3fb8aa3b, v64
	v_mul_f32_e32 v61, 0x3fb8aa3b, v61
	v_sub_f32_e32 v62, v33, v65
	v_mul_f32_e32 v65, 0x3fb8aa3b, v66
	v_sub_f32_e32 v63, v34, v66
	v_exp_f32_e32 v60, v20
	v_exp_f32_e32 v70, v69
	v_rcp_f32_e32 v64, v72
	v_exp_f32_e32 v61, v61
	v_exp_f32_e32 v71, v65
	v_mul_f32_e32 v63, 0x3fb8aa3b, v63
	v_rcp_f32_e32 v65, v73
	v_exp_f32_e32 v79, v63
	v_mul_f32_e32 v63, 0x3fb8aa3b, v67
	v_exp_f32_e32 v109, v63
	v_sub_f32_e32 v63, v35, v67
	v_lshlrev_b32_e32 v67, 16, v5
	v_lshlrev_b32_e32 v66, 16, v4
	v_pk_mul_f32 v[112:113], v[60:61], v[66:67]
	v_pk_mul_f32 v[114:115], v[72:73], v[110:111]
	v_pk_mul_f32 v[72:73], v[64:65], v[116:117]
	v_pk_mul_f32 v[64:65], v[70:71], v[66:67]
	s_waitcnt lgkmcnt(0)
; __device__ __forceinline__ float bflo(unsigned w) { return __uint_as_float(w << 16); }
; __device__ __forceinline__ float bfhi(unsigned w) { return __uint_as_float(w & 0xffff0000u); }
; __device__ __forceinline__ unsigned pk2(float lo, float hi) { return f2bf(lo) | (f2bf(hi) << 16); }
; __device__ __forceinline__ void phase_gla_pre(const Params& P, LAS unsigned char* lds, bool dry) {
;     ...
;             for (int e2 = 0; e2 < 8; ++e2) {
;                 const unsigned qw = e2 < 4 ? rq[0][e2] : rq[1][e2 - 4], kw = e2 < 4 ? rk[0][e2] : rk[1][e2 - 4];
;                 float vqi[2], vki[2], vqd[2], vks[2];
; #pragma unroll
;                 for (int hh = 0; hh < 2; ++hh) {
;                     const int e = 2 * e2 + hh; const float bv = bb[e >> 2][e & 3], bmv = bm[e >> 2][e & 3], blv = bl[e >> 2][e & 3];
;                     const float qv = hh ? bfhi(qw) : bflo(qw), kv = hh ? bfhi(kw) : bflo(kw);
;                     const float e1 = __expf(bv - bmv);
;                     vqi[hh] = qv * e1; vki[hh] = kv * __builtin_amdgcn_rcpf(e1); vqd[hh] = qv * __expf(bv); vks[hh] = kv * __expf(blv - bv);
;                 }
;                 oqi[e2] = pk2(vqi[0], vqi[1]); oki[e2] = pk2(vki[0], vki[1]); oqd[e2] = pk2(vqd[0], vqd[1]); oks[e2] = pk2(vks[0], vks[1]);
	v_sub_f32_e32 v66, v74, v100
	v_mul_f32_e32 v66, 0x3fb8aa3b, v66
	v_mul_f32_e32 v71, 0x3fb8aa3b, v74
	v_exp_f32_e32 v70, v66
	v_pk_mul_f32 v[66:67], v[108:109], v[110:111]
	v_exp_f32_e32 v108, v71
	v_sub_f32_e32 v71, v75, v101
	v_mul_f32_e32 v71, 0x3fb8aa3b, v71
	v_mul_f32_e32 v62, 0x3fb8aa3b, v62
	v_mul_f32_e32 v63, 0x3fb8aa3b, v63
	v_exp_f32_e32 v100, v71
	v_sub_f32_e32 v71, v24, v74
	v_exp_f32_e32 v62, v62
	v_exp_f32_e32 v63, v63
	v_mul_f32_e32 v71, 0x3fb8aa3b, v71
	v_exp_f32_e32 v74, v71
	v_mul_f32_e32 v71, 0x3fb8aa3b, v75
	v_sub_f32_e32 v75, v25, v75
	v_mul_f32_e32 v75, 0x3fb8aa3b, v75
	v_exp_f32_e32 v118, v75
	v_mul_f32_e32 v75, 0x3fb8aa3b, v76
	v_pk_mul_f32 v[62:63], v[62:63], v[116:117]
	v_exp_f32_e32 v116, v71
	v_sub_f32_e32 v71, v76, v102
	v_exp_f32_e32 v109, v75
	v_sub_f32_e32 v75, v77, v103
	v_mul_f32_e32 v71, 0x3fb8aa3b, v71
	v_mul_f32_e32 v75, 0x3fb8aa3b, v75
	v_rcp_f32_e32 v68, v60
	v_rcp_f32_e32 v69, v61
	v_exp_f32_e32 v71, v71
	v_exp_f32_e32 v101, v75
	v_sub_f32_e32 v75, v26, v76
	v_mul_f32_e32 v76, 0x3fb8aa3b, v77
	v_exp_f32_e32 v117, v76
	v_sub_f32_e32 v76, v27, v77
	v_mul_f32_e32 v76, 0x3fb8aa3b, v76
	v_lshlrev_b32_e32 v61, 16, v13
	v_lshlrev_b32_e32 v60, 16, v12
	v_exp_f32_e32 v119, v76
	v_lshlrev_b32_e32 v77, 16, v7
	v_lshlrev_b32_e32 v76, 16, v6
	v_pk_mul_f32 v[68:69], v[68:69], v[60:61]
	v_pk_mul_f32 v[60:61], v[78:79], v[60:61]
	v_rcp_f32_e32 v78, v70
	v_rcp_f32_e32 v110, v100
	v_rcp_f32_e32 v79, v71
	v_rcp_f32_e32 v111, v101
	v_pk_mul_f32 v[70:71], v[70:71], v[76:77]
	v_pk_mul_f32 v[100:101], v[100:101], v[120:121]
	v_cvt_pk_bf16_f32 v224, v112, v114
	v_cvt_pk_bf16_f32 v222, v113, v115
	v_cvt_pk_bf16_f32 v221, v70, v100
	v_cvt_pk_bf16_f32 v220, v71, v101
	ds_read_b128 v[104:107], v21 offset:51216
	ds_read_b128 v[40:43], v21 offset:51232
	ds_read_b128 v[28:31], v90
	ds_read_b128 v[20:23], v91
	v_mov_b32_e32 v103, v220
	v_mov_b32_e32 v102, v221
	v_lshlrev_b32_e32 v71, 16, v15
	v_lshlrev_b32_e32 v70, 16, v14
	v_mul_f32_e32 v75, 0x3fb8aa3b, v75
	v_mov_b32_e32 v101, v222
	v_mov_b32_e32 v100, v224
	v_pk_mul_f32 v[114:115], v[78:79], v[70:71]
	s_waitcnt lgkmcnt(3)
	v_sub_f32_e32 v78, v44, v104
	v_sub_f32_e32 v105, v45, v105
	v_exp_f32_e32 v75, v75
	v_mul_f32_e32 v78, 0x3fb8aa3b, v78
	v_mul_f32_e32 v105, 0x3fb8aa3b, v105
	v_exp_f32_e32 v104, v78
	v_pk_mul_f32 v[78:79], v[116:117], v[120:121]
	v_exp_f32_e32 v116, v105
	v_mul_f32_e32 v105, 0x3fb8aa3b, v45
	s_waitcnt lgkmcnt(1)
	v_sub_f32_e32 v45, v29, v45
	v_mul_f32_e32 v45, 0x3fb8aa3b, v45
	v_and_b32_e32 v113, 0xffff0000, v15
	v_and_b32_e32 v112, 0xffff0000, v14
	v_exp_f32_e32 v120, v105
	v_sub_f32_e32 v105, v46, v106
	v_exp_f32_e32 v106, v45
	v_mul_f32_e32 v45, 0x3fb8aa3b, v46
	v_pk_mul_f32 v[110:111], v[110:111], v[112:113]
	v_pk_mul_f32 v[70:71], v[74:75], v[70:71]
	v_pk_mul_f32 v[74:75], v[118:119], v[112:113]
	v_exp_f32_e32 v113, v45
	v_sub_f32_e32 v45, v47, v107
	v_mul_f32_e32 v45, 0x3fb8aa3b, v45
	v_exp_f32_e32 v117, v45
	v_sub_f32_e32 v45, v30, v46
	v_mul_f32_e32 v46, 0x3fb8aa3b, v47
	v_exp_f32_e32 v121, v46
	v_sub_f32_e32 v46, v31, v47
	v_pk_mul_f32 v[76:77], v[108:109], v[76:77]
	v_mul_f32_e32 v109, 0x3fb8aa3b, v44
	v_mul_f32_e32 v105, 0x3fb8aa3b, v105
	v_mul_f32_e32 v46, 0x3fb8aa3b, v46
	v_exp_f32_e32 v112, v109
	v_exp_f32_e32 v105, v105
	v_exp_f32_e32 v107, v46
	v_rcp_f32_e32 v118, v116
	v_rcp_f32_e32 v119, v117
	v_sub_f32_e32 v44, v28, v44
	v_lshlrev_b32_e32 v47, 16, v9
	v_lshlrev_b32_e32 v46, 16, v8
	v_rcp_f32_e32 v108, v104
	v_mul_f32_e32 v44, 0x3fb8aa3b, v44
	v_rcp_f32_e32 v109, v105
	v_mul_f32_e32 v45, 0x3fb8aa3b, v45
	v_pk_mul_f32 v[104:105], v[104:105], v[46:47]
	v_pk_mul_f32 v[112:113], v[112:113], v[46:47]
	v_sub_f32_e32 v40, v36, v40
	v_pk_mul_f32 v[46:47], v[106:107], v[126:127]
	v_mul_f32_e32 v107, 0x3fb8aa3b, v36
	s_waitcnt lgkmcnt(0)
; #define LAS __attribute__((address_space(3)))
; __device__ __forceinline__ unsigned pk2(float lo, float hi) { return f2bf(lo) | (f2bf(hi) << 16); }
; __device__ __forceinline__ void phase_gla_pre(const Params& P, LAS unsigned char* lds, bool dry) {
;     ...
;                     const float e1 = __expf(bv - bmv);
;                     vqi[hh] = qv * e1; vki[hh] = kv * __builtin_amdgcn_rcpf(e1); vqd[hh] = qv * __expf(bv); vks[hh] = kv * __expf(blv - bv);
;                 }
;                 oqi[e2] = pk2(vqi[0], vqi[1]); oki[e2] = pk2(vki[0], vki[1]); oqd[e2] = pk2(vqd[0], vqd[1]); oks[e2] = pk2(vks[0], vks[1]);
;             }
;             *(LAS u32x4*)(Lqi + te * QP + 32 * kc) = (u32x4){oqi[0], oqi[1], oqi[2], oqi[3]}; *(LAS u32x4*)(Lqi + te * QP + 32 * kc + 16) = (u32x4){oqi[4], oqi[5], oqi[6], oqi[7]};
;             *(LAS u32x4*)(Lki + te * QP + 32 * kc) = (u32x4){oki[0], oki[1], oki[2], oki[3]}; *(LAS u32x4*)(Lki + te * QP + 32 * kc + 16) = (u32x4){oki[4], oki[5], oki[6], oki[7]};
;             if (!dry) {
;                 bf16_t* p_ = PJ + ((size_t)bh * SEQ + c * 64 + te) * 128 + 16 * kc;
;                 *(u32x4*)(p_ + T_Q) = (u32x4){oqd[0], oqd[1], oqd[2], oqd[3]}; *(u32x4*)(p_ + T_Q + 8) = (u32x4){oqd[4], oqd[5], oqd[6], oqd[7]};
;                 *(u32x4*)(p_ + T_K) = (u32x4){oks[0], oks[1], oks[2], oks[3]}; *(u32x4*)(p_ + T_K + 8) = (u32x4){oks[4], oks[5], oks[6], oks[7]};
;                 if (te == 63) {
; #pragma unroll
;                     for (int i = 0; i < 4; ++i) *(f32x4*)(DEC + (size_t)item * 128 + 16 * kc + 4 * i) = (f32x4){__expf(bl[i][0]), __expf(bl[i][1]), __expf(bl[i][2]), __expf(bl[i][3])};
;                 }
	v_sub_f32_e32 v36, v20, v36
	v_exp_f32_e32 v44, v44
	v_exp_f32_e32 v45, v45
	v_mul_f32_e32 v36, 0x3fb8aa3b, v36
	v_pk_mul_f32 v[118:119], v[118:119], v[126:127]
	v_exp_f32_e32 v126, v36
	v_mul_f32_e32 v36, 0x3fb8aa3b, v37
	v_sub_f32_e32 v41, v37, v41
	v_exp_f32_e32 v130, v36
	v_sub_f32_e32 v36, v38, v42
	v_mul_f32_e32 v41, 0x3fb8aa3b, v41
	v_mul_f32_e32 v36, 0x3fb8aa3b, v36
	v_pk_mul_f32 v[108:109], v[108:109], v[124:125]
	v_pk_mul_f32 v[44:45], v[44:45], v[124:125]
	v_exp_f32_e32 v124, v41
	v_exp_f32_e32 v41, v36
	v_sub_f32_e32 v36, v21, v37
	v_mul_f32_e32 v36, 0x3fb8aa3b, v36
	v_and_b32_e32 v123, 0xffff0000, v9
	v_and_b32_e32 v122, 0xffff0000, v8
	v_exp_f32_e32 v42, v36
	v_mul_f32_e32 v36, 0x3fb8aa3b, v38
	v_pk_mul_f32 v[116:117], v[116:117], v[122:123]
	v_pk_mul_f32 v[120:121], v[120:121], v[122:123]
	v_exp_f32_e32 v123, v36
	v_sub_f32_e32 v36, v39, v43
	v_mul_f32_e32 v36, 0x3fb8aa3b, v36
	v_mul_f32_e32 v40, 0x3fb8aa3b, v40
	v_exp_f32_e32 v125, v36
	v_sub_f32_e32 v36, v22, v38
	v_exp_f32_e32 v40, v40
	v_mul_f32_e32 v36, 0x3fb8aa3b, v36
	v_exp_f32_e32 v127, v36
	v_mul_f32_e32 v36, 0x3fb8aa3b, v39
	v_exp_f32_e32 v131, v36
	v_sub_f32_e32 v36, v23, v39
	v_mul_f32_e32 v36, 0x3fb8aa3b, v36
	v_rcp_f32_e32 v128, v124
	v_rcp_f32_e32 v129, v125
	v_exp_f32_e32 v43, v36
	v_pk_mul_f32 v[36:37], v[40:41], v[132:133]
	v_pk_mul_f32 v[38:39], v[124:125], v[134:135]
	v_rcp_f32_e32 v106, v40
	v_exp_f32_e32 v122, v107
	v_rcp_f32_e32 v107, v41
	v_cvt_pk_bf16_f32 v228, v104, v116
	v_cvt_pk_bf16_f32 v227, v105, v117
	v_cvt_pk_bf16_f32 v226, v36, v38
	v_cvt_pk_bf16_f32 v225, v37, v39
	v_mov_b32_e32 v39, v225
	v_mov_b32_e32 v38, v226
	v_mov_b32_e32 v37, v227
	v_mov_b32_e32 v36, v228
	ds_write_b128 v92, v[100:103]
	ds_write_b128 v92, v[36:39] offset:16
	v_cvt_pk_bf16_f32 v230, v68, v72
	v_cvt_pk_bf16_f32 v229, v69, v73
	v_lshlrev_b32_e32 v41, 16, v19
	v_lshlrev_b32_e32 v40, 16, v18
	v_cvt_pk_bf16_f32 v39, v115, v111
	v_cvt_pk_bf16_f32 v38, v114, v110
	v_mov_b32_e32 v37, v229
	v_mov_b32_e32 v36, v230
	v_and_b32_e32 v105, 0xffff0000, v19
	v_and_b32_e32 v104, 0xffff0000, v18
	v_pk_mul_f32 v[106:107], v[106:107], v[40:41]
	ds_write_b128 v92, v[36:39] offset:17408
	v_pk_mul_f32 v[116:117], v[128:129], v[104:105]
	s_nop 0
	v_cvt_pk_bf16_f32 v39, v107, v117
	v_cvt_pk_bf16_f32 v38, v106, v116
	v_cvt_pk_bf16_f32 v37, v109, v119
	v_cvt_pk_bf16_f32 v36, v108, v118
	ds_write_b128 v92, v[36:39] offset:17424
	v_lshl_add_u64 v[36:37], s[74:75], 0, v[48:49]
	v_lshlrev_b64 v[36:37], 8, v[36:37]
	v_lshl_add_u64 v[38:39], v[52:53], 0, s[36:37]
	v_lshl_add_u64 v[68:69], v[38:39], 0, v[36:37]
	v_cvt_pk_bf16_f32 v232, v64, v66
	v_cvt_pk_bf16_f32 v233, v65, v67
	s_brev_b32 s36, 16
	v_cvt_pk_bf16_f32 v39, v77, v79
	v_mov_b32_e32 v36, v232
	v_add_co_u32_e32 v64, vcc, s36, v68
	v_cvt_pk_bf16_f32 v38, v76, v78
	v_mov_b32_e32 v37, v233
	v_addc_co_u32_e32 v65, vcc, 0, v69, vcc
	v_pk_mul_f32 v[122:123], v[122:123], v[132:133]
	global_store_dwordx4 v[64:65], v[36:39], off
	v_pk_mul_f32 v[124:125], v[130:131], v[134:135]
	s_nop 0
	v_cvt_pk_bf16_f32 v39, v123, v125
	v_cvt_pk_bf16_f32 v38, v122, v124
	v_cvt_pk_bf16_f32 v37, v113, v121
	v_cvt_pk_bf16_f32 v36, v112, v120
	global_store_dwordx4 v[64:65], v[36:39], off offset:16
	s_nop 1
	s_nop 0
	v_cvt_pk_bf16_f32 v234, v60, v62
	v_cvt_pk_bf16_f32 v235, v61, v63
	v_cvt_pk_bf16_f32 v39, v71, v75
	v_mov_b32_e32 v36, v234
	v_add_co_u32_e32 v60, vcc, s95, v68
	v_pk_mul_f32 v[42:43], v[42:43], v[104:105]
	v_cvt_pk_bf16_f32 v38, v70, v74
	v_mov_b32_e32 v37, v235
	v_addc_co_u32_e32 v61, vcc, 0, v69, vcc
	v_pk_mul_f32 v[40:41], v[126:127], v[40:41]
	global_store_dwordx4 v[60:61], v[36:39], off
	s_nop 1
	v_cvt_pk_bf16_f32 v240, v44, v46
	v_cvt_pk_bf16_f32 v239, v45, v47
	v_cvt_pk_bf16_f32 v238, v40, v42
	v_cvt_pk_bf16_f32 v237, v41, v43
	v_mov_b32_e32 v39, v237
	v_mov_b32_e32 v38, v238
	v_mov_b32_e32 v37, v239
	v_mov_b32_e32 v36, v240
	global_store_dwordx4 v[60:61], v[36:39], off offset:16
	s_and_saveexec_b64 s[36:37], s[12:13]
	s_cbranch_execz .LBB0_494
	v_mul_f32_e32 v32, 0x3fb8aa3b, v32
	v_mul_f32_e32 v33, 0x3fb8aa3b, v33
	v_mul_f32_e32 v34, 0x3fb8aa3b, v34
	v_mul_f32_e32 v35, 0x3fb8aa3b, v35
	v_exp_f32_e32 v32, v32
	v_exp_f32_e32 v33, v33
	v_exp_f32_e32 v34, v34
	v_exp_f32_e32 v35, v35
	v_mul_f32_e32 v24, 0x3fb8aa3b, v24
	v_mul_f32_e32 v25, 0x3fb8aa3b, v25
	v_mul_f32_e32 v26, 0x3fb8aa3b, v26
	v_mul_f32_e32 v27, 0x3fb8aa3b, v27
	s_ashr_i32 s81, s80, 31
	v_exp_f32_e32 v24, v24
	v_exp_f32_e32 v25, v25
	v_exp_f32_e32 v26, v26
	v_exp_f32_e32 v27, v27
	v_mul_f32_e32 v28, 0x3fb8aa3b, v28
	v_mul_f32_e32 v29, 0x3fb8aa3b, v29
	v_mul_f32_e32 v30, 0x3fb8aa3b, v30
	v_mul_f32_e32 v31, 0x3fb8aa3b, v31
	s_lshl_b64 s[42:43], s[80:81], 9
	v_exp_f32_e32 v28, v28
	v_exp_f32_e32 v29, v29
	v_exp_f32_e32 v30, v30
	v_exp_f32_e32 v31, v31
	v_mul_f32_e32 v20, 0x3fb8aa3b, v20
	v_mul_f32_e32 v21, 0x3fb8aa3b, v21
	v_mul_f32_e32 v22, 0x3fb8aa3b, v22
	v_mul_f32_e32 v23, 0x3fb8aa3b, v23
	v_lshl_add_u64 v[36:37], v[54:55], 0, s[42:43]
	v_exp_f32_e32 v20, v20
	v_exp_f32_e32 v21, v21
	v_exp_f32_e32 v22, v22
	v_exp_f32_e32 v23, v23
	global_store_dwordx4 v[36:37], v[32:35], off
	global_store_dwordx4 v[36:37], v[24:27], off offset:16
	global_store_dwordx4 v[36:37], v[28:31], off offset:32
	global_store_dwordx4 v[36:37], v[20:23], off offset:48
